# also P4 conv-tap staging (3 serial round trips -> 1) and P10 gain staging (4 -> 1) with all loads in flight; on top of v114
# baseline (speedup 1.0000x reference)
.LBB0_612:
	s_andn2_b64 vcc, exec, s[0:1]
	s_cbranch_vccnz .LBB0_630
	s_waitcnt vmcnt(0)
	s_mov_b64 s[0:1], exec
	v_lshlrev_b32_e32 v1, 2, v0
	v_add_u32_e32 v2, 0x1000, v1
	v_add_u32_e32 v3, 0x2000, v1
	v_add_u32_e32 v4, 0x3000, v1
	v_add_u32_e32 v5, 0x4000, v1
	v_add_u32_e32 v6, 0x5000, v1
	global_load_dword v10, v1, s[36:37]
	global_load_dword v11, v1, s[36:37] offset:2048
	global_load_dword v12, v2, s[36:37]
	global_load_dword v13, v2, s[36:37] offset:2048
	global_load_dword v14, v3, s[36:37]
	global_load_dword v15, v3, s[36:37] offset:2048
	global_load_dword v16, v4, s[36:37]
	global_load_dword v17, v4, s[36:37] offset:2048
	global_load_dword v18, v5, s[36:37]
	global_load_dword v19, v5, s[36:37] offset:2048
	global_load_dword v20, v6, s[36:37]
	global_load_dword v21, v6, s[36:37] offset:2048
	v_lshrrev_b32_e32 v7, 3, v0
	v_bfe_u32 v8, v0, 2, 1
	v_and_b32_e32 v9, 3, v0
	v_lshl_add_u32 v7, v7, 2, v9
	v_lshl_add_u32 v7, v8, 10, v7
	v_lshlrev_b32_e32 v7, 2, v7
	s_waitcnt vmcnt(0) lgkmcnt(0)
	ds_write_b32 v7, v10
	ds_write_b32 v7, v11 offset:1024
	ds_write_b32 v7, v12 offset:2048
	ds_write_b32 v7, v13 offset:3072
	ds_write_b32 v7, v14 offset:8192
	ds_write_b32 v7, v15 offset:9216
	ds_write_b32 v7, v16 offset:10240
	ds_write_b32 v7, v17 offset:11264
	ds_write_b32 v7, v18 offset:16384
	ds_write_b32 v7, v19 offset:17408
	ds_write_b32 v7, v20 offset:18432
	ds_write_b32 v7, v21 offset:19456

.LBB0_1149:
	s_andn2_b64 vcc, exec, s[0:1]
	s_cbranch_vccnz .LBB0_1166
	s_mov_b64 s[0:1], exec
	s_waitcnt vmcnt(0)
	v_lshlrev_b32_e32 v1, 2, v0
	v_add_u32_e32 v2, 0x1000, v1
	v_add_u32_e32 v3, 0x2000, v1
	v_add_u32_e32 v4, 0x3000, v1
	global_load_dword v10, v1, s[50:51]
	global_load_dword v11, v1, s[50:51] offset:2048
	global_load_dword v12, v2, s[50:51]
	global_load_dword v13, v2, s[50:51] offset:2048
	global_load_dword v14, v3, s[50:51]
	global_load_dword v15, v3, s[50:51] offset:2048
	global_load_dword v16, v4, s[50:51]
	global_load_dword v17, v4, s[50:51] offset:2048
	s_waitcnt vmcnt(0) lgkmcnt(0)
	ds_write_b32 v1, v10
	ds_write_b32 v1, v11 offset:2048
	ds_write_b32 v1, v12 offset:4096
	ds_write_b32 v1, v13 offset:6144
	ds_write_b32 v1, v14 offset:8192
	ds_write_b32 v1, v15 offset:10240
	ds_write_b32 v1, v16 offset:12288
	ds_write_b32 v1, v17 offset:14336
